# P0b tail W-quant rows: next row prefetched while current row is quantised
# baseline (speedup 1.0000x reference)
; __device__ __forceinline__ void phase_norm(Frame& F, const Params& p, int which) {
;     ...
;         for (int rw0 = gw; rw0 < INW + D; rw0 += NGW) {
;             const bool isq = rw0 >= INW; const int rw = isq ? rw0 - INW : rw0;
;             const u32x4* src = (const u32x4*)((const bf16*)(F.ws + (isq ? WS_WQ : WS_WIN)) + (size_t)rw * D) + F.lane;
;             u32x2* dst = (u32x2*)(F.ws + (isq ? WS_WQI8 : WS_WINI8) + (size_t)rw * D) + F.lane;
;             u32x4 w[4]; float cm = 0.f;
; #pragma unroll
;             for (int j = 0; j < 4; ++j) {
;                 w[j] = src[64 * j];
.LBB0_309:
	s_cmpk_gt_i32 s60, 0x23ff
	s_cbranch_scc1 .LBB0_314
	v_xor_b32_e32 v0, 4, v40
	v_xor_b32_e32 v1, 8, v40
	v_xor_b32_e32 v2, 16, v40
	v_xor_b32_e32 v3, 32, v40
	v_xor_b32_e32 v4, 64, v40
	v_xor_b32_e32 v5, 0x80, v40
	v_cmp_eq_u32_e64 s[4:5], 0, v28
	s_mov_b32 s16, 0x3600000
	s_mov_b32 s17, 0x9000000
	s_mov_b32 s18, 0x42fe0000
	s_mov_b32 s19, 0x40c0c00
	s_mov_b32 s28, 0x18000
	v_mov_b32_e32 v6, 0
	s_mov_b32 s29, s60
	s_add_i32 s12, s29, 0xffffe400
	s_cmpk_gt_i32 s29, 0x1bff
	s_cselect_b32 s7, s16, 0x800000
	s_cselect_b32 s6, s12, s29
	s_add_u32 s35, s56, s7
	s_addc_u32 s36, s57, 0
	s_ashr_i32 s7, s6, 31
	s_lshl_b64 s[30:31], s[6:7], 12
	s_add_u32 s30, s35, s30
	s_addc_u32 s31, s36, s31
	v_lshl_add_u64 v[206:207], v[28:29], 4, s[30:31]
	global_load_dwordx4 v[208:211], v[206:207], off
	global_load_dwordx4 v[212:215], v[206:207], off offset:1024
	global_load_dwordx4 v[216:219], v[206:207], off offset:2048
	global_load_dwordx4 v[220:223], v[206:207], off offset:3072
	s_waitcnt vmcnt(0)
	s_branch .Lmy_wq_enter

; __device__ __forceinline__ float bf_lo(unsigned w) { return __uint_as_float(w << 16); }
; __device__ __forceinline__ float bf_hi(unsigned w) { return __uint_as_float(w & 0xffff0000u); }
; __device__ __forceinline__ float shx(float v, int o, int lane) { return __int_as_float(__builtin_amdgcn_ds_bpermute((lane ^ o) << 2, __float_as_int(v))); }
; __device__ __forceinline__ int shx(int v, int o, int lane) { return __builtin_amdgcn_ds_bpermute((lane ^ o) << 2, v); }
; __device__ __forceinline__ void phase_norm(Frame& F, const Params& p, int which) {
;     ...
;         for (int rw0 = gw; rw0 < INW + D; rw0 += NGW) {
;             const bool isq = rw0 >= INW; const int rw = isq ? rw0 - INW : rw0;
;             const u32x4* src = (const u32x4*)((const bf16*)(F.ws + (isq ? WS_WQ : WS_WIN)) + (size_t)rw * D) + F.lane;
;             u32x2* dst = (u32x2*)(F.ws + (isq ? WS_WQI8 : WS_WINI8) + (size_t)rw * D) + F.lane;
;             u32x4 w[4]; float cm = 0.f;
; #pragma unroll
;             for (int j = 0; j < 4; ++j) {
;                 w[j] = src[64 * j];
;                 cm = fmaxf(cm, fmaxf(fmaxf(fmaxf(fabsf(bf_lo(w[j].x)), fabsf(bf_hi(w[j].x))), fmaxf(fabsf(bf_lo(w[j].y)), fabsf(bf_hi(w[j].y)))),
;                                      fmaxf(fmaxf(fabsf(bf_lo(w[j].z)), fabsf(bf_hi(w[j].z))), fmaxf(fabsf(bf_lo(w[j].w)), fabsf(bf_hi(w[j].w))))));
;             }
; #pragma unroll
;             for (int o = 1; o < 64; o <<= 1) cm = fmaxf(cm, shx(cm, o, F.lane));
.LBB0_312:
	s_waitcnt vmcnt(4)
.Lmy_wq_enter:
	v_mov_b32_e32 v8, v208
	v_mov_b32_e32 v9, v209
	v_mov_b32_e32 v10, v210
	v_mov_b32_e32 v11, v211
	v_mov_b32_e32 v12, v212
	v_mov_b32_e32 v13, v213
	v_mov_b32_e32 v14, v214
	v_mov_b32_e32 v15, v215
	v_mov_b32_e32 v16, v216
	v_mov_b32_e32 v17, v217
	v_mov_b32_e32 v18, v218
	v_mov_b32_e32 v19, v219
	v_mov_b32_e32 v20, v220
	v_mov_b32_e32 v21, v221
	v_mov_b32_e32 v22, v222
	v_mov_b32_e32 v23, v223
	s_add_i32 s6, s29, s54
	s_cmpk_lt_i32 s6, 0x2400
	s_cbranch_scc0 .Lmy_wq_nonext
	s_mov_b32 s34, s6
	s_add_i32 s12, s34, 0xffffe400
	s_cmpk_gt_i32 s34, 0x1bff
	s_cselect_b32 s7, s16, 0x800000
	s_cselect_b32 s6, s12, s34
	s_add_u32 s35, s56, s7
	s_addc_u32 s36, s57, 0
	s_ashr_i32 s7, s6, 31
	s_lshl_b64 s[30:31], s[6:7], 12
	s_add_u32 s30, s35, s30
	s_addc_u32 s31, s36, s31
	v_lshl_add_u64 v[206:207], v[28:29], 4, s[30:31]
	global_load_dwordx4 v[208:211], v[206:207], off
	global_load_dwordx4 v[212:215], v[206:207], off offset:1024
	global_load_dwordx4 v[216:219], v[206:207], off offset:2048
	global_load_dwordx4 v[220:223], v[206:207], off offset:3072
.Lmy_wq_nonext:
	s_add_i32 s12, s29, 0xffffe400
	s_cmpk_gt_i32 s29, 0x1bff
	s_cselect_b64 s[10:11], -1, 0
	s_and_b64 s[6:7], s[10:11], exec
	s_cselect_b32 s7, s16, 0x800000
	s_cselect_b32 s6, s12, s29
	s_cselect_b32 s34, s17, 0x10000000
	s_add_u32 s35, s56, s7
	s_addc_u32 s36, s57, 0
	s_ashr_i32 s7, s6, 31
	s_lshl_b64 s[12:13], s[6:7], 11
	s_lshl_b64 s[30:31], s[6:7], 12
	s_add_u32 s30, s35, s30
	s_addc_u32 s31, s36, s31
	s_add_u32 s30, s56, s34
	s_addc_u32 s31, s57, 0
	s_add_u32 s12, s30, s12
	s_addc_u32 s13, s31, s13
	v_lshlrev_b32_e32 v24, 16, v8
	v_and_b32_e32 v25, 0xffff0000, v8
	v_lshlrev_b32_e32 v26, 16, v9
	v_and_b32_e32 v27, 0xffff0000, v9
	v_lshlrev_b32_e32 v31, 16, v11
	v_and_b32_e32 v11, 0xffff0000, v11
	v_lshlrev_b32_e32 v35, 16, v15
	v_and_b32_e32 v15, 0xffff0000, v15
	v_lshlrev_b32_e32 v32, 16, v12
	v_and_b32_e32 v12, 0xffff0000, v12
	v_lshlrev_b32_e32 v33, 16, v13
	v_and_b32_e32 v13, 0xffff0000, v13
	v_lshlrev_b32_e32 v39, 16, v19
	v_and_b32_e32 v19, 0xffff0000, v19
	v_lshlrev_b32_e32 v43, 16, v23
	v_and_b32_e32 v23, 0xffff0000, v23
	v_max_f32_e64 v7, |v25|, |v25|
	v_max_f32_e64 v8, |v24|, |v24|
	v_max_f32_e64 v9, |v27|, |v27|
	v_max_f32_e64 v44, |v26|, |v26|
	v_max_f32_e64 v45, |v11|, |v11|
	v_max_f32_e64 v46, |v31|, |v31|
	v_max_f32_e64 v51, |v15|, |v15|
	v_max_f32_e64 v52, |v35|, |v35|
	v_lshlrev_b32_e32 v30, 16, v10
	v_and_b32_e32 v10, 0xffff0000, v10
	v_lshlrev_b32_e32 v34, 16, v14
	v_and_b32_e32 v14, 0xffff0000, v14
	v_lshlrev_b32_e32 v36, 16, v16
	v_and_b32_e32 v16, 0xffff0000, v16
	v_lshlrev_b32_e32 v37, 16, v17
	v_and_b32_e32 v17, 0xffff0000, v17
	v_lshlrev_b32_e32 v40, 16, v20
	v_and_b32_e32 v20, 0xffff0000, v20
	v_lshlrev_b32_e32 v41, 16, v21
	v_and_b32_e32 v21, 0xffff0000, v21
	v_max_f32_e64 v47, |v12|, |v12|
	v_max_f32_e64 v48, |v32|, |v32|
	v_max_f32_e64 v49, |v13|, |v13|
	v_max_f32_e64 v50, |v33|, |v33|
	v_max_f32_e64 v57, |v19|, |v19|
	v_max_f32_e64 v58, |v39|, |v39|
	v_max_f32_e64 v63, |v23|, |v23|
	v_max_f32_e64 v64, |v43|, |v43|
	v_max_f32_e32 v7, v8, v7
	v_max_f32_e32 v8, v44, v9
	v_max_f32_e32 v9, v46, v45
	v_max_f32_e32 v46, v52, v51
	v_lshlrev_b32_e32 v38, 16, v18
	v_and_b32_e32 v18, 0xffff0000, v18
	v_lshlrev_b32_e32 v42, 16, v22
	v_and_b32_e32 v22, 0xffff0000, v22
	v_max_f32_e64 v53, |v16|, |v16|
	v_max_f32_e64 v54, |v36|, |v36|
	v_max_f32_e64 v55, |v17|, |v17|
	v_max_f32_e64 v56, |v37|, |v37|
	v_max_f32_e64 v59, |v20|, |v20|
	v_max_f32_e64 v60, |v40|, |v40|
	v_max_f32_e64 v61, |v21|, |v21|
	v_max_f32_e64 v62, |v41|, |v41|
	v_max_f32_e32 v44, v48, v47
	v_max_f32_e32 v45, v50, v49
	v_max_f32_e32 v49, v58, v57
	v_max_f32_e32 v52, v64, v63
	v_max3_f32 v9, |v30|, |v10|, v9
	v_max3_f32 v46, |v34|, |v14|, v46
	v_max_f32_e32 v47, v54, v53
	v_max_f32_e32 v48, v56, v55
	v_max_f32_e32 v50, v60, v59
	v_max_f32_e32 v51, v62, v61
	v_max3_f32 v49, |v38|, |v18|, v49
	v_max3_f32 v52, |v42|, |v22|, v52
	v_max3_f32 v7, v7, v8, v9
	v_max3_f32 v8, v44, v45, v46
	v_max3_f32 v9, v47, v48, v49
	v_max3_f32 v44, v50, v51, v52
	v_max3_f32 v7, v7, 0, v8
	v_max3_f32 v7, v7, v9, v44
	ds_bpermute_b32 v8, v0, v7
	s_waitcnt lgkmcnt(0)
	v_max_f32_e32 v8, v8, v8
	v_max_f32_e32 v7, v7, v8
	ds_bpermute_b32 v8, v1, v7
	s_waitcnt lgkmcnt(0)
	v_max_f32_e32 v8, v8, v8
	v_max_f32_e32 v7, v7, v8
	ds_bpermute_b32 v8, v2, v7
	s_waitcnt lgkmcnt(0)
	v_max_f32_e32 v8, v8, v8
	v_max_f32_e32 v7, v7, v8
	ds_bpermute_b32 v8, v3, v7
	s_waitcnt lgkmcnt(0)
	v_max_f32_e32 v8, v8, v8
	v_max_f32_e32 v7, v7, v8
	ds_bpermute_b32 v8, v4, v7
	s_waitcnt lgkmcnt(0)
	v_max_f32_e32 v8, v8, v8
	v_max_f32_e32 v7, v7, v8
	ds_bpermute_b32 v8, v5, v7
	s_waitcnt lgkmcnt(0)
; __device__ __forceinline__ float bf_lo(unsigned w) { return __uint_as_float(w << 16); }
; __device__ __forceinline__ float bf_hi(unsigned w) { return __uint_as_float(w & 0xffff0000u); }
; __device__ __forceinline__ float shx(float v, int o, int lane) { return __int_as_float(__builtin_amdgcn_ds_bpermute((lane ^ o) << 2, __float_as_int(v))); }
; __device__ __forceinline__ int shx(int v, int o, int lane) { return __builtin_amdgcn_ds_bpermute((lane ^ o) << 2, v); }
; __device__ __forceinline__ void phase_norm(Frame& F, const Params& p, int which) {
;     ...
;             for (int o = 1; o < 64; o <<= 1) cm = fmaxf(cm, shx(cm, o, F.lane));
;             const float inv = cm > 0.f ? 127.f / cm : 0.f;
; #pragma unroll
;             for (int j = 0; j < 4; ++j) {
;                 const int q0 = (int)rintf(bf_lo(w[j].x) * inv), q1 = (int)rintf(bf_hi(w[j].x) * inv), q2 = (int)rintf(bf_lo(w[j].y) * inv), q3 = (int)rintf(bf_hi(w[j].y) * inv);
;                 const int q4 = (int)rintf(bf_lo(w[j].z) * inv), q5 = (int)rintf(bf_hi(w[j].z) * inv), q6 = (int)rintf(bf_lo(w[j].w) * inv), q7 = (int)rintf(bf_hi(w[j].w) * inv);
;                 u32x2 o; o.x = (unsigned)(q0 & 255) | ((unsigned)(q1 & 255) << 8) | ((unsigned)(q2 & 255) << 16) | ((unsigned)(q3 & 255) << 24);
;                 o.y = (unsigned)(q4 & 255) | ((unsigned)(q5 & 255) << 8) | ((unsigned)(q6 & 255) << 16) | ((unsigned)(q7 & 255) << 24);
;                 dst[64 * j] = o;
;             }
;             if (F.lane == 0) ((float*)(F.ws + (isq ? WS_CMAXQ : WS_CMAX)))[rw] = cm;
;         }
	v_max_f32_e32 v8, v8, v8
	v_max_f32_e32 v7, v7, v8
	v_div_scale_f32 v44, s[30:31], v7, v7, s18
	v_rcp_f32_e32 v45, v44
	v_div_scale_f32 v46, vcc, s18, v7, s18
	v_lshl_add_u64 v[8:9], v[28:29], 3, s[12:13]
	v_fma_f32 v47, -v44, v45, 1.0
	v_fmac_f32_e32 v45, v47, v45
	v_mul_f32_e32 v47, v46, v45
	v_fma_f32 v48, -v44, v47, v46
	v_fmac_f32_e32 v47, v48, v45
	v_fma_f32 v44, -v44, v47, v46
	v_div_fmas_f32 v44, v44, v45, v47
	v_div_fixup_f32 v44, v44, v7, s18
	v_cmp_lt_f32_e32 vcc, 0, v7
	s_nop 1
	v_cndmask_b32_e32 v44, 0, v44, vcc
	v_mul_f32_e32 v25, v44, v25
	v_mul_f32_e32 v24, v44, v24
	v_mul_f32_e32 v26, v44, v26
	v_mul_f32_e32 v27, v44, v27
	v_rndne_f32_e32 v25, v25
	v_mul_f32_e32 v10, v44, v10
	v_rndne_f32_e32 v24, v24
	v_rndne_f32_e32 v26, v26
	v_rndne_f32_e32 v27, v27
	v_cvt_i32_f32_e32 v25, v25
	v_mul_f32_e32 v30, v44, v30
	v_mul_f32_e32 v31, v44, v31
	v_mul_f32_e32 v11, v44, v11
	v_rndne_f32_e32 v10, v10
	v_cvt_i32_f32_e32 v24, v24
	v_cvt_i32_f32_sdwa v26, v26 dst_sel:WORD_1 dst_unused:UNUSED_PAD src0_sel:DWORD
	v_cvt_i32_f32_e32 v27, v27
	v_rndne_f32_e32 v30, v30
	v_rndne_f32_e32 v31, v31
	v_rndne_f32_e32 v11, v11
	v_cvt_i32_f32_e32 v45, v10
	v_cvt_i32_f32_e32 v30, v30
	v_cvt_i32_f32_sdwa v31, v31 dst_sel:WORD_1 dst_unused:UNUSED_PAD src0_sel:DWORD
	v_cvt_i32_f32_e32 v11, v11
	v_lshlrev_b32_e32 v10, 8, v25
	v_and_b32_e32 v10, 0xff00, v10
	v_and_b32_e32 v25, 0xff0000, v26
	v_perm_b32 v24, v27, v24, s19
	v_or3_b32 v10, v24, v10, v25
	v_lshlrev_b32_e32 v24, 8, v45
	v_and_b32_e32 v24, 0xff00, v24
	v_and_b32_e32 v25, 0xff0000, v31
	v_perm_b32 v11, v11, v30, s19
	v_or3_b32 v11, v11, v24, v25
	global_store_dwordx2 v[8:9], v[10:11], off
	v_mul_f32_e32 v11, v44, v12
	v_mul_f32_e32 v10, v44, v32
	v_rndne_f32_e32 v11, v11
	v_mul_f32_e32 v12, v44, v33
	v_mul_f32_e32 v13, v44, v13
	v_rndne_f32_e32 v10, v10
	v_cvt_i32_f32_e32 v11, v11
	v_rndne_f32_e32 v12, v12
	v_rndne_f32_e32 v13, v13
	v_mul_f32_e32 v14, v44, v14
	v_cvt_i32_f32_e32 v10, v10
	v_cvt_i32_f32_sdwa v12, v12 dst_sel:WORD_1 dst_unused:UNUSED_PAD src0_sel:DWORD
	v_cvt_i32_f32_e32 v13, v13
	v_mul_f32_e32 v24, v44, v34
	v_rndne_f32_e32 v14, v14
	v_mul_f32_e32 v25, v44, v35
	v_mul_f32_e32 v15, v44, v15
	v_rndne_f32_e32 v24, v24
	v_cvt_i32_f32_e32 v14, v14
	v_rndne_f32_e32 v25, v25
	v_rndne_f32_e32 v15, v15
	v_cvt_i32_f32_e32 v24, v24
	v_cvt_i32_f32_sdwa v25, v25 dst_sel:WORD_1 dst_unused:UNUSED_PAD src0_sel:DWORD
	v_cvt_i32_f32_e32 v15, v15
	v_lshlrev_b32_e32 v11, 8, v11
	v_and_b32_e32 v11, 0xff00, v11
	v_and_b32_e32 v12, 0xff0000, v12
	v_perm_b32 v10, v13, v10, s19
	v_or3_b32 v10, v10, v11, v12
	v_lshlrev_b32_e32 v11, 8, v14
	v_and_b32_e32 v11, 0xff00, v11
	v_and_b32_e32 v12, 0xff0000, v25
	v_perm_b32 v13, v15, v24, s19
	v_or3_b32 v11, v13, v11, v12
	global_store_dwordx2 v[8:9], v[10:11], off offset:512
	v_mul_f32_e32 v11, v44, v16
	v_mul_f32_e32 v10, v44, v36
	v_rndne_f32_e32 v11, v11
	v_mul_f32_e32 v12, v44, v37
	v_mul_f32_e32 v13, v44, v17
	v_rndne_f32_e32 v10, v10
	v_cvt_i32_f32_e32 v11, v11
	v_rndne_f32_e32 v12, v12
	v_rndne_f32_e32 v13, v13
	v_mul_f32_e32 v15, v44, v18
	v_cvt_i32_f32_e32 v10, v10
	v_cvt_i32_f32_sdwa v12, v12 dst_sel:WORD_1 dst_unused:UNUSED_PAD src0_sel:DWORD
	v_cvt_i32_f32_e32 v13, v13
	v_mul_f32_e32 v14, v44, v38
	v_rndne_f32_e32 v15, v15
	v_mul_f32_e32 v16, v44, v39
	v_mul_f32_e32 v17, v44, v19
	v_rndne_f32_e32 v14, v14
	v_cvt_i32_f32_e32 v15, v15
	v_rndne_f32_e32 v16, v16
	v_rndne_f32_e32 v17, v17
	v_cvt_i32_f32_e32 v14, v14
	v_cvt_i32_f32_sdwa v16, v16 dst_sel:WORD_1 dst_unused:UNUSED_PAD src0_sel:DWORD
	v_cvt_i32_f32_e32 v17, v17
	v_lshlrev_b32_e32 v11, 8, v11
	v_and_b32_e32 v11, 0xff00, v11
	v_and_b32_e32 v12, 0xff0000, v12
	v_perm_b32 v10, v13, v10, s19
	v_or3_b32 v10, v10, v11, v12
	v_lshlrev_b32_e32 v11, 8, v15
	v_and_b32_e32 v11, 0xff00, v11
	v_and_b32_e32 v12, 0xff0000, v16
	v_perm_b32 v13, v17, v14, s19
	v_or3_b32 v11, v13, v11, v12
	global_store_dwordx2 v[8:9], v[10:11], off offset:1024
	v_mul_f32_e32 v11, v44, v20
	v_mul_f32_e32 v10, v44, v40
	v_rndne_f32_e32 v11, v11
	v_mul_f32_e32 v12, v44, v41
	v_mul_f32_e32 v13, v44, v21
	v_rndne_f32_e32 v10, v10
	v_cvt_i32_f32_e32 v11, v11
	v_rndne_f32_e32 v12, v12
	v_rndne_f32_e32 v13, v13
	v_mul_f32_e32 v15, v44, v22
	v_cvt_i32_f32_e32 v10, v10
	v_cvt_i32_f32_sdwa v12, v12 dst_sel:WORD_1 dst_unused:UNUSED_PAD src0_sel:DWORD
	v_cvt_i32_f32_e32 v13, v13
	v_mul_f32_e32 v14, v44, v42
	v_rndne_f32_e32 v15, v15
	v_mul_f32_e32 v16, v44, v43
	v_mul_f32_e32 v17, v44, v23
	v_rndne_f32_e32 v14, v14
	v_cvt_i32_f32_e32 v15, v15
	v_rndne_f32_e32 v16, v16
	v_rndne_f32_e32 v17, v17
	v_cvt_i32_f32_e32 v14, v14
	v_cvt_i32_f32_sdwa v16, v16 dst_sel:WORD_1 dst_unused:UNUSED_PAD src0_sel:DWORD
	v_cvt_i32_f32_e32 v17, v17
	v_lshlrev_b32_e32 v11, 8, v11
	v_and_b32_e32 v11, 0xff00, v11
	v_and_b32_e32 v12, 0xff0000, v12
	v_perm_b32 v10, v13, v10, s19
	v_or3_b32 v10, v10, v11, v12
	v_lshlrev_b32_e32 v11, 8, v15
	v_and_b32_e32 v11, 0xff00, v11
	v_and_b32_e32 v12, 0xff0000, v16
	v_perm_b32 v13, v17, v14, s19
	v_or3_b32 v11, v13, v11, v12
	global_store_dwordx2 v[8:9], v[10:11], off offset:1536
	s_and_saveexec_b64 s[12:13], s[4:5]
	s_cbranch_execz .LBB0_311
	s_and_b64 s[10:11], s[10:11], exec
	s_cselect_b32 s10, s28, 0x10000
	s_add_u32 s10, s56, s10
	s_addc_u32 s11, s57, 0
	s_lshl_b64 s[6:7], s[6:7], 2
	s_add_u32 s6, s10, s6
	s_addc_u32 s7, s11, s7
	global_store_dword v6, v7, s[6:7]
	s_branch .LBB0_311
